# cross-tile prefetch in ev_in and ffup K-loops: the next tile's stage-0/1 LDS-DMA loads are issued from the current tile's last two K stages (before the epilogue), first wait counts the epilogue stores
# speedup vs baseline: 1.0030x; 1.0013x over previous
_Z4mega6Params:
	v_writelane_b32 v251, 0, 0
	s_load_dwordx8 s[36:43], s[0:1], 0xc0
	s_load_dwordx4 s[88:91], s[0:1], 0xe0
	s_load_dwordx2 s[92:93], s[0:1], 0xf0
	s_add_u32 s4, s0, 0xf0
	v_and_b32_e32 v128, 0x3ff, v0
	s_mov_b32 s33, s2
	s_addc_u32 s5, s1, 0
	v_cmp_eq_u32_e64 s[34:35], 0, v128
	s_and_saveexec_b64 s[2:3], s[34:35]
	s_cbranch_execz .LBB0_2
	v_mov_b32_e32 v2, 0
	v_mov_b32_e32 v3, v2
	v_mov_b32_e32 v4, v2
	v_mov_b32_e32 v5, v2
	v_mov_b32_e32 v1, 0x13000
	ds_write_b128 v1, v[2:5]

.LBB0_260:
	s_mul_hi_i32 s0, s23, 0x2aaaaaab
	s_lshr_b32 s1, s0, 31
	s_ashr_i32 s4, s0, 4
	s_add_i32 s4, s4, s1
	s_mul_i32 s0, s4, 0x60
	s_sub_i32 s0, s23, s0
	s_lshl_b32 s13, s0, 7
	s_lshl_b32 s14, s4, 7
	v_lshl_or_b32 v64, v183, 3, v191
	v_and_b32_e32 v65, 63, v64
	v_lshrrev_b32_e32 v66, 3, v65
	v_lshrrev_b32_e32 v67, 4, v65
	v_xor_b32_e32 v67, v67, v65
	v_and_b32_e32 v67, 7, v67
	v_lshlrev_b32_e32 v67, 4, v67
	s_movk_i32 s99, 0x800
	v_mad_u32_u24 v112, v66, s99, v67
	v_xor_b32_e32 v68, 64, v112
	v_add_u32_e32 v113, 0x3c00, v68
	v_add_u32_e32 v114, 0x7800, v112
	v_add_u32_e32 v115, 0xb400, v68
	v_add_u32_e32 v116, 0x10000, v112
	v_add_u32_e32 v117, 0x13c00, v68
	v_add_u32_e32 v118, 0x17800, v112
	v_add_u32_e32 v119, 0x1b400, v68
	v_and_b32_e32 v69, 31, v64
	v_bfe_u32 v70, v64, 5, 1
	v_bfe_u32 v71, v64, 1, 3
	v_xor_b32_e32 v71, v71, v70
	v_lshlrev_b32_e32 v71, 4, v71
	v_bfe_u32 v72, v64, 7, 1
	v_lshl_or_b32 v72, v72, 6, v69
	v_lshl_add_u32 v120, v72, 7, v71
	v_bfe_u32 v73, v64, 6, 1
	v_lshl_or_b32 v73, v73, 6, v69
	v_lshl_add_u32 v124, v73, 7, v71
	v_add_u32_e32 v124, 0x4000, v124
	v_xor_b32_e32 v121, 32, v120
	v_xor_b32_e32 v125, 32, v124
	v_xor_b32_e32 v122, 64, v120
	v_xor_b32_e32 v126, 64, v124
	v_xor_b32_e32 v123, 96, v120
	v_xor_b32_e32 v127, 96, v124
	v_lshrrev_b32_e32 v74, 6, v64
	s_nop 0
	v_readfirstlane_b32 s100, v74
	s_nop 3
	s_lshl_b32 s98, s100, 13
	s_mov_b32 s101, 0x0
	s_mov_b32 s99, s14
	s_cmp_lt_u32 s100, 2
	s_cmov_b32 s101, 0xb171900
	s_cmov_b32 s99, s13
	s_and_b32 s100, s100, 1
	s_lshl_b32 s100, s100, 6
	s_add_u32 s99, s99, s100
	s_mul_i32 s99, s99, 0x800
	s_add_u32 s99, s99, s101
	s_add_u32 s0, s90, s99
	s_addc_u32 s1, s91, 0
	v_readlane_b32 s99, v251, 0
	s_cmp_lg_u32 s99, 0
	s_cbranch_scc1 .Lg1_pref
	s_add_u32 m0, s98, 0x0
	s_nop 0
	global_load_lds_dwordx4 v112, s[0:1] offset:0
	global_load_lds_dwordx4 v113, s[0:1] offset:1024
	global_load_lds_dwordx4 v114, s[0:1] offset:2048
	global_load_lds_dwordx4 v115, s[0:1] offset:3072
	s_add_u32 m0, s98, 0x1000
	s_nop 0
	global_load_lds_dwordx4 v116, s[0:1] offset:0
	global_load_lds_dwordx4 v117, s[0:1] offset:1024
	global_load_lds_dwordx4 v118, s[0:1] offset:2048
	global_load_lds_dwordx4 v119, s[0:1] offset:3072
	s_add_u32 s0, s0, 0x80
	s_addc_u32 s1, s1, 0
	s_add_u32 m0, s98, 0x8000
	s_nop 0
	global_load_lds_dwordx4 v112, s[0:1] offset:0
	global_load_lds_dwordx4 v113, s[0:1] offset:1024
	global_load_lds_dwordx4 v114, s[0:1] offset:2048
	global_load_lds_dwordx4 v115, s[0:1] offset:3072
	s_add_u32 m0, s98, 0x9000
	s_nop 0
	global_load_lds_dwordx4 v116, s[0:1] offset:0
	global_load_lds_dwordx4 v117, s[0:1] offset:1024
	global_load_lds_dwordx4 v118, s[0:1] offset:2048
	global_load_lds_dwordx4 v119, s[0:1] offset:3072
	s_add_u32 s0, s0, 0x80
	s_addc_u32 s1, s1, 0
	s_mov_b32 s101, 0
	s_branch .Lg1_prol
.Lg1_pref:
	s_add_u32 s0, s0, 0x100
	s_addc_u32 s1, s1, 0
	s_mov_b32 s101, 1
.Lg1_prol:
	v_mov_b32_e32 v48, 0
	v_mov_b32_e32 v49, 0
	v_mov_b32_e32 v50, 0
	v_mov_b32_e32 v51, 0
	v_mov_b32_e32 v52, 0
	v_mov_b32_e32 v53, 0
	v_mov_b32_e32 v54, 0
	v_mov_b32_e32 v55, 0
	v_mov_b32_e32 v56, 0
	v_mov_b32_e32 v57, 0
	v_mov_b32_e32 v58, 0
	v_mov_b32_e32 v59, 0
	v_mov_b32_e32 v60, 0
	v_mov_b32_e32 v61, 0
	v_mov_b32_e32 v62, 0
	v_mov_b32_e32 v63, 0
	v_mov_b32_e32 v16, 0
	v_mov_b32_e32 v17, 0
	v_mov_b32_e32 v18, 0
	v_mov_b32_e32 v19, 0
	v_mov_b32_e32 v20, 0
	v_mov_b32_e32 v21, 0
	v_mov_b32_e32 v22, 0
	v_mov_b32_e32 v23, 0
	v_mov_b32_e32 v24, 0
	v_mov_b32_e32 v25, 0
	v_mov_b32_e32 v26, 0
	v_mov_b32_e32 v27, 0
	v_mov_b32_e32 v28, 0
	v_mov_b32_e32 v29, 0
	v_mov_b32_e32 v30, 0
	v_mov_b32_e32 v31, 0
	v_mov_b32_e32 v32, 0
	v_mov_b32_e32 v33, 0
	v_mov_b32_e32 v34, 0
	v_mov_b32_e32 v35, 0
	v_mov_b32_e32 v36, 0
	v_mov_b32_e32 v37, 0
	v_mov_b32_e32 v38, 0
	v_mov_b32_e32 v39, 0
	v_mov_b32_e32 v40, 0
	v_mov_b32_e32 v41, 0
	v_mov_b32_e32 v42, 0
	v_mov_b32_e32 v43, 0
	v_mov_b32_e32 v44, 0
	v_mov_b32_e32 v45, 0
	v_mov_b32_e32 v46, 0
	v_mov_b32_e32 v47, 0
	v_mov_b32_e32 v0, 0
	v_mov_b32_e32 v1, 0
	v_mov_b32_e32 v2, 0
	v_mov_b32_e32 v3, 0
	v_mov_b32_e32 v4, 0
	v_mov_b32_e32 v5, 0
	v_mov_b32_e32 v6, 0
	v_mov_b32_e32 v7, 0
	v_mov_b32_e32 v8, 0
	v_mov_b32_e32 v9, 0
	v_mov_b32_e32 v10, 0
	v_mov_b32_e32 v11, 0
	v_mov_b32_e32 v12, 0
	v_mov_b32_e32 v13, 0
	v_mov_b32_e32 v14, 0
	v_mov_b32_e32 v15, 0
	s_movk_i32 s2, 7
	s_cmp_lg_u32 s101, 0
	s_cbranch_scc1 .Lg1_w0p
	s_waitcnt vmcnt(8)
	s_branch .Lg1_loop
.Lg1_w0p:
	s_waitcnt vmcnt(16)
.Lg1_loop:
	s_barrier
	ds_read_b128 v[64:67], v120 offset:0
	ds_read_b128 v[72:75], v124 offset:0
	ds_read_b128 v[76:79], v124 offset:4096
	ds_read_b128 v[68:71], v120 offset:4096
	ds_read_b128 v[80:83], v121 offset:0
	ds_read_b128 v[88:91], v125 offset:0
	ds_read_b128 v[92:95], v125 offset:4096
	ds_read_b128 v[84:87], v121 offset:4096
	s_waitcnt lgkmcnt(4)
	v_mfma_f32_32x32x16_bf16 v[48:63], v[64:67], v[72:75], v[48:63]
	ds_read_b128 v[96:99], v122 offset:0
	v_mfma_f32_32x32x16_bf16 v[16:31], v[64:67], v[76:79], v[16:31]
	ds_read_b128 v[104:107], v126 offset:0
	v_mfma_f32_32x32x16_bf16 v[32:47], v[68:71], v[72:75], v[32:47]
	ds_read_b128 v[108:111], v126 offset:4096
	v_mfma_f32_32x32x16_bf16 v[0:15], v[68:71], v[76:79], v[0:15]
	ds_read_b128 v[100:103], v122 offset:4096
	s_waitcnt lgkmcnt(4)
	v_mfma_f32_32x32x16_bf16 v[48:63], v[80:83], v[88:91], v[48:63]
	ds_read_b128 v[64:67], v123 offset:0
	v_mfma_f32_32x32x16_bf16 v[16:31], v[80:83], v[92:95], v[16:31]
	ds_read_b128 v[72:75], v127 offset:0
	v_mfma_f32_32x32x16_bf16 v[32:47], v[84:87], v[88:91], v[32:47]
	ds_read_b128 v[76:79], v127 offset:4096
	v_mfma_f32_32x32x16_bf16 v[0:15], v[84:87], v[92:95], v[0:15]
	ds_read_b128 v[68:71], v123 offset:4096
	s_waitcnt lgkmcnt(4)
	v_mfma_f32_32x32x16_bf16 v[48:63], v[96:99], v[104:107], v[48:63]
	v_mfma_f32_32x32x16_bf16 v[16:31], v[96:99], v[108:111], v[16:31]
	v_mfma_f32_32x32x16_bf16 v[32:47], v[100:103], v[104:107], v[32:47]
	v_mfma_f32_32x32x16_bf16 v[0:15], v[100:103], v[108:111], v[0:15]
	s_waitcnt lgkmcnt(0)
	v_mfma_f32_32x32x16_bf16 v[48:63], v[64:67], v[72:75], v[48:63]
	v_mfma_f32_32x32x16_bf16 v[16:31], v[64:67], v[76:79], v[16:31]
	v_mfma_f32_32x32x16_bf16 v[32:47], v[68:71], v[72:75], v[32:47]
	v_mfma_f32_32x32x16_bf16 v[0:15], v[68:71], v[76:79], v[0:15]
	s_barrier
	s_add_u32 m0, s98, 0x0
	s_nop 0
	global_load_lds_dwordx4 v112, s[0:1] offset:0
	global_load_lds_dwordx4 v113, s[0:1] offset:1024
	global_load_lds_dwordx4 v114, s[0:1] offset:2048
	global_load_lds_dwordx4 v115, s[0:1] offset:3072
	s_add_u32 m0, s98, 0x1000
	s_nop 0
	global_load_lds_dwordx4 v116, s[0:1] offset:0
	global_load_lds_dwordx4 v117, s[0:1] offset:1024
	global_load_lds_dwordx4 v118, s[0:1] offset:2048
	global_load_lds_dwordx4 v119, s[0:1] offset:3072
	s_add_u32 s0, s0, 0x80
	s_addc_u32 s1, s1, 0
	s_waitcnt vmcnt(8)
	s_barrier
	ds_read_b128 v[64:67], v120 offset:32768
	ds_read_b128 v[72:75], v124 offset:32768
	ds_read_b128 v[76:79], v124 offset:36864
	ds_read_b128 v[68:71], v120 offset:36864
	ds_read_b128 v[80:83], v121 offset:32768
	ds_read_b128 v[88:91], v125 offset:32768
	ds_read_b128 v[92:95], v125 offset:36864
	ds_read_b128 v[84:87], v121 offset:36864
	s_waitcnt lgkmcnt(4)
	v_mfma_f32_32x32x16_bf16 v[48:63], v[64:67], v[72:75], v[48:63]
	ds_read_b128 v[96:99], v122 offset:32768
	v_mfma_f32_32x32x16_bf16 v[16:31], v[64:67], v[76:79], v[16:31]
	ds_read_b128 v[104:107], v126 offset:32768
	v_mfma_f32_32x32x16_bf16 v[32:47], v[68:71], v[72:75], v[32:47]
	ds_read_b128 v[108:111], v126 offset:36864
	v_mfma_f32_32x32x16_bf16 v[0:15], v[68:71], v[76:79], v[0:15]
	ds_read_b128 v[100:103], v122 offset:36864
	s_waitcnt lgkmcnt(4)
	v_mfma_f32_32x32x16_bf16 v[48:63], v[80:83], v[88:91], v[48:63]
	ds_read_b128 v[64:67], v123 offset:32768
	v_mfma_f32_32x32x16_bf16 v[16:31], v[80:83], v[92:95], v[16:31]
	ds_read_b128 v[72:75], v127 offset:32768
	v_mfma_f32_32x32x16_bf16 v[32:47], v[84:87], v[88:91], v[32:47]
	ds_read_b128 v[76:79], v127 offset:36864
	v_mfma_f32_32x32x16_bf16 v[0:15], v[84:87], v[92:95], v[0:15]
	ds_read_b128 v[68:71], v123 offset:36864
	s_waitcnt lgkmcnt(4)
	v_mfma_f32_32x32x16_bf16 v[48:63], v[96:99], v[104:107], v[48:63]
	v_mfma_f32_32x32x16_bf16 v[16:31], v[96:99], v[108:111], v[16:31]
	v_mfma_f32_32x32x16_bf16 v[32:47], v[100:103], v[104:107], v[32:47]
	v_mfma_f32_32x32x16_bf16 v[0:15], v[100:103], v[108:111], v[0:15]
	s_waitcnt lgkmcnt(0)
	v_mfma_f32_32x32x16_bf16 v[48:63], v[64:67], v[72:75], v[48:63]
	v_mfma_f32_32x32x16_bf16 v[16:31], v[64:67], v[76:79], v[16:31]
	v_mfma_f32_32x32x16_bf16 v[32:47], v[68:71], v[72:75], v[32:47]
	v_mfma_f32_32x32x16_bf16 v[0:15], v[68:71], v[76:79], v[0:15]
	s_barrier
	s_add_u32 m0, s98, 0x8000
	s_nop 0
	global_load_lds_dwordx4 v112, s[0:1] offset:0
	global_load_lds_dwordx4 v113, s[0:1] offset:1024
	global_load_lds_dwordx4 v114, s[0:1] offset:2048
	global_load_lds_dwordx4 v115, s[0:1] offset:3072
	s_add_u32 m0, s98, 0x9000
	s_nop 0
	global_load_lds_dwordx4 v116, s[0:1] offset:0
	global_load_lds_dwordx4 v117, s[0:1] offset:1024
	global_load_lds_dwordx4 v118, s[0:1] offset:2048
	global_load_lds_dwordx4 v119, s[0:1] offset:3072
	s_add_u32 s0, s0, 0x80
	s_addc_u32 s1, s1, 0
	s_sub_u32 s2, s2, 1
	s_waitcnt vmcnt(8)
	s_cmp_lg_u32 s2, 0
	s_cbranch_scc1 .Lg1_loop
	s_barrier
	ds_read_b128 v[64:67], v120 offset:0
	ds_read_b128 v[72:75], v124 offset:0
	ds_read_b128 v[76:79], v124 offset:4096
	ds_read_b128 v[68:71], v120 offset:4096
	ds_read_b128 v[80:83], v121 offset:0
	ds_read_b128 v[88:91], v125 offset:0
	ds_read_b128 v[92:95], v125 offset:4096
	ds_read_b128 v[84:87], v121 offset:4096
	s_waitcnt lgkmcnt(4)
	v_mfma_f32_32x32x16_bf16 v[48:63], v[64:67], v[72:75], v[48:63]
	ds_read_b128 v[96:99], v122 offset:0
	v_mfma_f32_32x32x16_bf16 v[16:31], v[64:67], v[76:79], v[16:31]
	ds_read_b128 v[104:107], v126 offset:0
	v_mfma_f32_32x32x16_bf16 v[32:47], v[68:71], v[72:75], v[32:47]
	ds_read_b128 v[108:111], v126 offset:4096
	v_mfma_f32_32x32x16_bf16 v[0:15], v[68:71], v[76:79], v[0:15]
	ds_read_b128 v[100:103], v122 offset:4096
	s_waitcnt lgkmcnt(4)
	v_mfma_f32_32x32x16_bf16 v[48:63], v[80:83], v[88:91], v[48:63]
	ds_read_b128 v[64:67], v123 offset:0
	v_mfma_f32_32x32x16_bf16 v[16:31], v[80:83], v[92:95], v[16:31]
	ds_read_b128 v[72:75], v127 offset:0
	v_mfma_f32_32x32x16_bf16 v[32:47], v[84:87], v[88:91], v[32:47]
	ds_read_b128 v[76:79], v127 offset:4096
	v_mfma_f32_32x32x16_bf16 v[0:15], v[84:87], v[92:95], v[0:15]
	ds_read_b128 v[68:71], v123 offset:4096
	s_waitcnt lgkmcnt(4)
	v_mfma_f32_32x32x16_bf16 v[48:63], v[96:99], v[104:107], v[48:63]
	v_mfma_f32_32x32x16_bf16 v[16:31], v[96:99], v[108:111], v[16:31]
	v_mfma_f32_32x32x16_bf16 v[32:47], v[100:103], v[104:107], v[32:47]
	v_mfma_f32_32x32x16_bf16 v[0:15], v[100:103], v[108:111], v[0:15]
	s_waitcnt lgkmcnt(0)
	v_mfma_f32_32x32x16_bf16 v[48:63], v[64:67], v[72:75], v[48:63]
	v_mfma_f32_32x32x16_bf16 v[16:31], v[64:67], v[76:79], v[16:31]
	v_mfma_f32_32x32x16_bf16 v[32:47], v[68:71], v[72:75], v[32:47]
	v_mfma_f32_32x32x16_bf16 v[0:15], v[68:71], v[76:79], v[0:15]
	s_barrier
	s_add_i32 s99, s23, s92
	s_mov_b32 s2, 0
	s_cmp_gt_i32 s99, 0xddf
	s_cbranch_scc1 .Lg1_nonext
	s_mul_hi_u32 s100, s99, 0xaaaaaaab
	s_lshr_b32 s100, s100, 6
	s_mul_i32 s101, s100, 0x60
	s_sub_u32 s101, s99, s101
	s_lshl_b32 s101, s101, 7
	s_lshl_b32 s100, s100, 7
	s_sub_i32 s101, s101, s13
	s_sub_i32 s100, s100, s14
	s_lshr_b32 s2, s98, 13
	s_cmp_lt_u32 s2, 2
	s_cselect_b32 s2, s101, s100
	s_mul_i32 s2, s2, 0x800
	s_sub_i32 s2, s2, 0x800
	s_ashr_i32 s101, s2, 31
	s_add_u32 s0, s0, s2
	s_addc_u32 s1, s1, s101
	s_add_u32 m0, s98, 0x0
	s_nop 0
	global_load_lds_dwordx4 v112, s[0:1] offset:0
	global_load_lds_dwordx4 v113, s[0:1] offset:1024
	global_load_lds_dwordx4 v114, s[0:1] offset:2048
	global_load_lds_dwordx4 v115, s[0:1] offset:3072
	s_add_u32 m0, s98, 0x1000
	s_nop 0
	global_load_lds_dwordx4 v116, s[0:1] offset:0
	global_load_lds_dwordx4 v117, s[0:1] offset:1024
	global_load_lds_dwordx4 v118, s[0:1] offset:2048
	global_load_lds_dwordx4 v119, s[0:1] offset:3072
	s_add_u32 s0, s0, 0x80
	s_addc_u32 s1, s1, 0
	s_mov_b32 s2, 1
.Lg1_nonext:
	s_cmp_lg_u32 s2, 0
	s_cbranch_scc1 .Lg1_w15p
	s_waitcnt vmcnt(0)
	s_branch .Lg1_s15

.Lg1_s15:
	s_barrier
	ds_read_b128 v[64:67], v120 offset:32768
	ds_read_b128 v[72:75], v124 offset:32768
	ds_read_b128 v[76:79], v124 offset:36864
	ds_read_b128 v[68:71], v120 offset:36864
	ds_read_b128 v[80:83], v121 offset:32768
	ds_read_b128 v[88:91], v125 offset:32768
	ds_read_b128 v[92:95], v125 offset:36864
	ds_read_b128 v[84:87], v121 offset:36864
	s_waitcnt lgkmcnt(4)
	v_mfma_f32_32x32x16_bf16 v[48:63], v[64:67], v[72:75], v[48:63]
	ds_read_b128 v[96:99], v122 offset:32768
	v_mfma_f32_32x32x16_bf16 v[16:31], v[64:67], v[76:79], v[16:31]
	ds_read_b128 v[104:107], v126 offset:32768
	v_mfma_f32_32x32x16_bf16 v[32:47], v[68:71], v[72:75], v[32:47]
	ds_read_b128 v[108:111], v126 offset:36864
	v_mfma_f32_32x32x16_bf16 v[0:15], v[68:71], v[76:79], v[0:15]
	ds_read_b128 v[100:103], v122 offset:36864
	s_waitcnt lgkmcnt(4)
	v_mfma_f32_32x32x16_bf16 v[48:63], v[80:83], v[88:91], v[48:63]
	ds_read_b128 v[64:67], v123 offset:32768
	v_mfma_f32_32x32x16_bf16 v[16:31], v[80:83], v[92:95], v[16:31]
	ds_read_b128 v[72:75], v127 offset:32768
	v_mfma_f32_32x32x16_bf16 v[32:47], v[84:87], v[88:91], v[32:47]
	ds_read_b128 v[76:79], v127 offset:36864
	v_mfma_f32_32x32x16_bf16 v[0:15], v[84:87], v[92:95], v[0:15]
	ds_read_b128 v[68:71], v123 offset:36864
	s_waitcnt lgkmcnt(4)
	v_mfma_f32_32x32x16_bf16 v[48:63], v[96:99], v[104:107], v[48:63]
	v_mfma_f32_32x32x16_bf16 v[16:31], v[96:99], v[108:111], v[16:31]
	v_mfma_f32_32x32x16_bf16 v[32:47], v[100:103], v[104:107], v[32:47]
	v_mfma_f32_32x32x16_bf16 v[0:15], v[100:103], v[108:111], v[0:15]
	s_waitcnt lgkmcnt(0)
	v_mfma_f32_32x32x16_bf16 v[48:63], v[64:67], v[72:75], v[48:63]
	v_mfma_f32_32x32x16_bf16 v[16:31], v[64:67], v[76:79], v[16:31]
	v_mfma_f32_32x32x16_bf16 v[32:47], v[68:71], v[72:75], v[32:47]
	v_mfma_f32_32x32x16_bf16 v[0:15], v[68:71], v[76:79], v[0:15]
	s_barrier
	v_writelane_b32 v251, s2, 0
	s_cmp_lg_u32 s2, 0
	s_cbranch_scc0 .Lg1_done
	s_add_u32 m0, s98, 0x8000
	s_nop 0
	global_load_lds_dwordx4 v112, s[0:1] offset:0
	global_load_lds_dwordx4 v113, s[0:1] offset:1024
	global_load_lds_dwordx4 v114, s[0:1] offset:2048
	global_load_lds_dwordx4 v115, s[0:1] offset:3072
	s_add_u32 m0, s98, 0x9000
	s_nop 0
	global_load_lds_dwordx4 v116, s[0:1] offset:0
	global_load_lds_dwordx4 v117, s[0:1] offset:1024
	global_load_lds_dwordx4 v118, s[0:1] offset:2048
	global_load_lds_dwordx4 v119, s[0:1] offset:3072
	s_add_u32 s0, s0, 0x80
	s_addc_u32 s1, s1, 0
.Lg1_done:
	s_nop 7
	s_nop 7
	s_branch .LBB0_268

.LBB0_1035:
	s_and_b32 s2, s57, 7
	s_bfe_u32 s3, s57, 0x60003
	s_lshr_b32 s6, s57, 9
	s_lshl_b32 s6, s6, 6
	s_add_u32 s3, s3, s6
	s_mul_hi_u32 s6, s3, 0xaaaaaaab
	s_lshr_b32 s6, s6, 3
	s_mul_i32 s7, s6, 12
	s_sub_u32 s3, s3, s7
	s_mul_i32 s2, s2, 12
	s_add_u32 s2, s2, s3
	s_lshl_b32 s48, s2, 7
	s_lshl_b32 s49, s6, 7
	v_lshl_or_b32 v64, v183, 3, v191
	v_and_b32_e32 v65, 63, v64
	v_lshrrev_b32_e32 v66, 3, v65
	v_lshrrev_b32_e32 v67, 4, v65
	v_xor_b32_e32 v67, v67, v65
	v_and_b32_e32 v67, 7, v67
	v_lshlrev_b32_e32 v67, 4, v67
	s_movk_i32 s99, 0x800
	v_mad_u32_u24 v112, v66, s99, v67
	v_xor_b32_e32 v68, 64, v112
	v_add_u32_e32 v113, 0x3c00, v68
	v_add_u32_e32 v114, 0x7800, v112
	v_add_u32_e32 v115, 0xb400, v68
	v_add_u32_e32 v116, 0x10000, v112
	v_add_u32_e32 v117, 0x13c00, v68
	v_add_u32_e32 v118, 0x17800, v112
	v_add_u32_e32 v119, 0x1b400, v68
	v_and_b32_e32 v69, 31, v64
	v_bfe_u32 v70, v64, 5, 1
	v_bfe_u32 v71, v64, 1, 3
	v_xor_b32_e32 v71, v71, v70
	v_lshlrev_b32_e32 v71, 4, v71
	v_bfe_u32 v72, v64, 7, 1
	v_lshl_or_b32 v72, v72, 6, v69
	v_lshl_add_u32 v120, v72, 7, v71
	v_bfe_u32 v73, v64, 6, 1
	v_lshl_or_b32 v73, v73, 6, v69
	v_lshl_add_u32 v124, v73, 7, v71
	v_add_u32_e32 v124, 0x4000, v124
	v_xor_b32_e32 v121, 32, v120
	v_xor_b32_e32 v125, 32, v124
	v_xor_b32_e32 v122, 64, v120
	v_xor_b32_e32 v126, 64, v124
	v_xor_b32_e32 v123, 96, v120
	v_xor_b32_e32 v127, 96, v124
	v_lshrrev_b32_e32 v74, 6, v64
	s_nop 0
	v_readfirstlane_b32 s100, v74
	s_nop 3
	s_lshl_b32 s98, s100, 13
	s_mov_b32 s101, 0xb40000
	s_mov_b32 s99, s49
	s_cmp_lt_u32 s100, 2
	s_cmov_b32 s101, 0xb171900
	s_cmov_b32 s99, s48
	s_and_b32 s100, s100, 1
	s_lshl_b32 s100, s100, 6
	s_add_u32 s99, s99, s100
	s_mul_i32 s99, s99, 0x800
	s_add_u32 s99, s99, s101
	s_add_u32 s2, s90, s99
	s_addc_u32 s3, s91, 0
	v_readlane_b32 s99, v251, 0
	s_cmp_lg_u32 s99, 0
	s_cbranch_scc1 .Lg2_pref
	s_add_u32 m0, s98, 0x0
	s_nop 0
	global_load_lds_dwordx4 v112, s[2:3] offset:0
	global_load_lds_dwordx4 v113, s[2:3] offset:1024
	global_load_lds_dwordx4 v114, s[2:3] offset:2048
	global_load_lds_dwordx4 v115, s[2:3] offset:3072
	s_add_u32 m0, s98, 0x1000
	s_nop 0
	global_load_lds_dwordx4 v116, s[2:3] offset:0
	global_load_lds_dwordx4 v117, s[2:3] offset:1024
	global_load_lds_dwordx4 v118, s[2:3] offset:2048
	global_load_lds_dwordx4 v119, s[2:3] offset:3072
	s_add_u32 s2, s2, 0x80
	s_addc_u32 s3, s3, 0
	s_add_u32 m0, s98, 0x8000
	s_nop 0
	global_load_lds_dwordx4 v112, s[2:3] offset:0
	global_load_lds_dwordx4 v113, s[2:3] offset:1024
	global_load_lds_dwordx4 v114, s[2:3] offset:2048
	global_load_lds_dwordx4 v115, s[2:3] offset:3072
	s_add_u32 m0, s98, 0x9000
	s_nop 0
	global_load_lds_dwordx4 v116, s[2:3] offset:0
	global_load_lds_dwordx4 v117, s[2:3] offset:1024
	global_load_lds_dwordx4 v118, s[2:3] offset:2048
	global_load_lds_dwordx4 v119, s[2:3] offset:3072
	s_add_u32 s2, s2, 0x80
	s_addc_u32 s3, s3, 0
	s_mov_b32 s101, 0
	s_branch .Lg2_prol
.Lg2_pref:
	s_add_u32 s2, s2, 0x100
	s_addc_u32 s3, s3, 0
	s_mov_b32 s101, 1
.Lg2_prol:
	v_mov_b32_e32 v48, 0
	v_mov_b32_e32 v49, 0
	v_mov_b32_e32 v50, 0
	v_mov_b32_e32 v51, 0
	v_mov_b32_e32 v52, 0
	v_mov_b32_e32 v53, 0
	v_mov_b32_e32 v54, 0
	v_mov_b32_e32 v55, 0
	v_mov_b32_e32 v56, 0
	v_mov_b32_e32 v57, 0
	v_mov_b32_e32 v58, 0
	v_mov_b32_e32 v59, 0
	v_mov_b32_e32 v60, 0
	v_mov_b32_e32 v61, 0
	v_mov_b32_e32 v62, 0
	v_mov_b32_e32 v63, 0
	v_mov_b32_e32 v32, 0
	v_mov_b32_e32 v33, 0
	v_mov_b32_e32 v34, 0
	v_mov_b32_e32 v35, 0
	v_mov_b32_e32 v36, 0
	v_mov_b32_e32 v37, 0
	v_mov_b32_e32 v38, 0
	v_mov_b32_e32 v39, 0
	v_mov_b32_e32 v40, 0
	v_mov_b32_e32 v41, 0
	v_mov_b32_e32 v42, 0
	v_mov_b32_e32 v43, 0
	v_mov_b32_e32 v44, 0
	v_mov_b32_e32 v45, 0
	v_mov_b32_e32 v46, 0
	v_mov_b32_e32 v47, 0
	v_mov_b32_e32 v16, 0
	v_mov_b32_e32 v17, 0
	v_mov_b32_e32 v18, 0
	v_mov_b32_e32 v19, 0
	v_mov_b32_e32 v20, 0
	v_mov_b32_e32 v21, 0
	v_mov_b32_e32 v22, 0
	v_mov_b32_e32 v23, 0
	v_mov_b32_e32 v24, 0
	v_mov_b32_e32 v25, 0
	v_mov_b32_e32 v26, 0
	v_mov_b32_e32 v27, 0
	v_mov_b32_e32 v28, 0
	v_mov_b32_e32 v29, 0
	v_mov_b32_e32 v30, 0
	v_mov_b32_e32 v31, 0
	v_mov_b32_e32 v0, 0
	v_mov_b32_e32 v1, 0
	v_mov_b32_e32 v2, 0
	v_mov_b32_e32 v3, 0
	v_mov_b32_e32 v4, 0
	v_mov_b32_e32 v5, 0
	v_mov_b32_e32 v6, 0
	v_mov_b32_e32 v7, 0
	v_mov_b32_e32 v8, 0
	v_mov_b32_e32 v9, 0
	v_mov_b32_e32 v10, 0
	v_mov_b32_e32 v11, 0
	v_mov_b32_e32 v12, 0
	v_mov_b32_e32 v13, 0
	v_mov_b32_e32 v14, 0
	v_mov_b32_e32 v15, 0
	s_movk_i32 s6, 7
	s_cmp_lg_u32 s101, 0
	s_cbranch_scc1 .Lg2_w0p
	s_waitcnt vmcnt(8)
	s_branch .Lg2_loop
.Lg2_w0p:
	s_waitcnt vmcnt(12)
.Lg2_loop:
	s_barrier
	ds_read_b128 v[64:67], v120 offset:0
	ds_read_b128 v[72:75], v124 offset:0
	ds_read_b128 v[76:79], v124 offset:4096
	ds_read_b128 v[68:71], v120 offset:4096
	ds_read_b128 v[80:83], v121 offset:0
	ds_read_b128 v[88:91], v125 offset:0
	ds_read_b128 v[92:95], v125 offset:4096
	ds_read_b128 v[84:87], v121 offset:4096
	s_waitcnt lgkmcnt(4)
	v_mfma_f32_32x32x16_bf16 v[48:63], v[64:67], v[72:75], v[48:63]
	ds_read_b128 v[96:99], v122 offset:0
	v_mfma_f32_32x32x16_bf16 v[32:47], v[64:67], v[76:79], v[32:47]
	ds_read_b128 v[104:107], v126 offset:0
	v_mfma_f32_32x32x16_bf16 v[16:31], v[68:71], v[72:75], v[16:31]
	ds_read_b128 v[108:111], v126 offset:4096
	v_mfma_f32_32x32x16_bf16 v[0:15], v[68:71], v[76:79], v[0:15]
	ds_read_b128 v[100:103], v122 offset:4096
	s_waitcnt lgkmcnt(4)
	v_mfma_f32_32x32x16_bf16 v[48:63], v[80:83], v[88:91], v[48:63]
	ds_read_b128 v[64:67], v123 offset:0
	v_mfma_f32_32x32x16_bf16 v[32:47], v[80:83], v[92:95], v[32:47]
	ds_read_b128 v[72:75], v127 offset:0
	v_mfma_f32_32x32x16_bf16 v[16:31], v[84:87], v[88:91], v[16:31]
	ds_read_b128 v[76:79], v127 offset:4096
	v_mfma_f32_32x32x16_bf16 v[0:15], v[84:87], v[92:95], v[0:15]
	ds_read_b128 v[68:71], v123 offset:4096
	s_waitcnt lgkmcnt(4)
	v_mfma_f32_32x32x16_bf16 v[48:63], v[96:99], v[104:107], v[48:63]
	v_mfma_f32_32x32x16_bf16 v[32:47], v[96:99], v[108:111], v[32:47]
	v_mfma_f32_32x32x16_bf16 v[16:31], v[100:103], v[104:107], v[16:31]
	v_mfma_f32_32x32x16_bf16 v[0:15], v[100:103], v[108:111], v[0:15]
	s_waitcnt lgkmcnt(0)
	v_mfma_f32_32x32x16_bf16 v[48:63], v[64:67], v[72:75], v[48:63]
	v_mfma_f32_32x32x16_bf16 v[32:47], v[64:67], v[76:79], v[32:47]
	v_mfma_f32_32x32x16_bf16 v[16:31], v[68:71], v[72:75], v[16:31]
	v_mfma_f32_32x32x16_bf16 v[0:15], v[68:71], v[76:79], v[0:15]
	s_barrier
	s_add_u32 m0, s98, 0x0
	s_nop 0
	global_load_lds_dwordx4 v112, s[2:3] offset:0
	global_load_lds_dwordx4 v113, s[2:3] offset:1024
	global_load_lds_dwordx4 v114, s[2:3] offset:2048
	global_load_lds_dwordx4 v115, s[2:3] offset:3072
	s_add_u32 m0, s98, 0x1000
	s_nop 0
	global_load_lds_dwordx4 v116, s[2:3] offset:0
	global_load_lds_dwordx4 v117, s[2:3] offset:1024
	global_load_lds_dwordx4 v118, s[2:3] offset:2048
	global_load_lds_dwordx4 v119, s[2:3] offset:3072
	s_add_u32 s2, s2, 0x80
	s_addc_u32 s3, s3, 0
	s_waitcnt vmcnt(8)
	s_barrier
	ds_read_b128 v[64:67], v120 offset:32768
	ds_read_b128 v[72:75], v124 offset:32768
	ds_read_b128 v[76:79], v124 offset:36864
	ds_read_b128 v[68:71], v120 offset:36864
	ds_read_b128 v[80:83], v121 offset:32768
	ds_read_b128 v[88:91], v125 offset:32768
	ds_read_b128 v[92:95], v125 offset:36864
	ds_read_b128 v[84:87], v121 offset:36864
	s_waitcnt lgkmcnt(4)
	v_mfma_f32_32x32x16_bf16 v[48:63], v[64:67], v[72:75], v[48:63]
	ds_read_b128 v[96:99], v122 offset:32768
	v_mfma_f32_32x32x16_bf16 v[32:47], v[64:67], v[76:79], v[32:47]
	ds_read_b128 v[104:107], v126 offset:32768
	v_mfma_f32_32x32x16_bf16 v[16:31], v[68:71], v[72:75], v[16:31]
	ds_read_b128 v[108:111], v126 offset:36864
	v_mfma_f32_32x32x16_bf16 v[0:15], v[68:71], v[76:79], v[0:15]
	ds_read_b128 v[100:103], v122 offset:36864
	s_waitcnt lgkmcnt(4)
	v_mfma_f32_32x32x16_bf16 v[48:63], v[80:83], v[88:91], v[48:63]
	ds_read_b128 v[64:67], v123 offset:32768
	v_mfma_f32_32x32x16_bf16 v[32:47], v[80:83], v[92:95], v[32:47]
	ds_read_b128 v[72:75], v127 offset:32768
	v_mfma_f32_32x32x16_bf16 v[16:31], v[84:87], v[88:91], v[16:31]
	ds_read_b128 v[76:79], v127 offset:36864
	v_mfma_f32_32x32x16_bf16 v[0:15], v[84:87], v[92:95], v[0:15]
	ds_read_b128 v[68:71], v123 offset:36864
	s_waitcnt lgkmcnt(4)
	v_mfma_f32_32x32x16_bf16 v[48:63], v[96:99], v[104:107], v[48:63]
	v_mfma_f32_32x32x16_bf16 v[32:47], v[96:99], v[108:111], v[32:47]
	v_mfma_f32_32x32x16_bf16 v[16:31], v[100:103], v[104:107], v[16:31]
	v_mfma_f32_32x32x16_bf16 v[0:15], v[100:103], v[108:111], v[0:15]
	s_waitcnt lgkmcnt(0)
	v_mfma_f32_32x32x16_bf16 v[48:63], v[64:67], v[72:75], v[48:63]
	v_mfma_f32_32x32x16_bf16 v[32:47], v[64:67], v[76:79], v[32:47]
	v_mfma_f32_32x32x16_bf16 v[16:31], v[68:71], v[72:75], v[16:31]
	v_mfma_f32_32x32x16_bf16 v[0:15], v[68:71], v[76:79], v[0:15]
	s_barrier
	s_add_u32 m0, s98, 0x8000
	s_nop 0
	global_load_lds_dwordx4 v112, s[2:3] offset:0
	global_load_lds_dwordx4 v113, s[2:3] offset:1024
	global_load_lds_dwordx4 v114, s[2:3] offset:2048
	global_load_lds_dwordx4 v115, s[2:3] offset:3072
	s_add_u32 m0, s98, 0x9000
	s_nop 0
	global_load_lds_dwordx4 v116, s[2:3] offset:0
	global_load_lds_dwordx4 v117, s[2:3] offset:1024
	global_load_lds_dwordx4 v118, s[2:3] offset:2048
	global_load_lds_dwordx4 v119, s[2:3] offset:3072
	s_add_u32 s2, s2, 0x80
	s_addc_u32 s3, s3, 0
	s_sub_u32 s6, s6, 1
	s_waitcnt vmcnt(8)
	s_cmp_lg_u32 s6, 0
	s_cbranch_scc1 .Lg2_loop
	s_barrier
	ds_read_b128 v[64:67], v120 offset:0
	ds_read_b128 v[72:75], v124 offset:0
	ds_read_b128 v[76:79], v124 offset:4096
	ds_read_b128 v[68:71], v120 offset:4096
	ds_read_b128 v[80:83], v121 offset:0
	ds_read_b128 v[88:91], v125 offset:0
	ds_read_b128 v[92:95], v125 offset:4096
	ds_read_b128 v[84:87], v121 offset:4096
	s_waitcnt lgkmcnt(4)
	v_mfma_f32_32x32x16_bf16 v[48:63], v[64:67], v[72:75], v[48:63]
	ds_read_b128 v[96:99], v122 offset:0
	v_mfma_f32_32x32x16_bf16 v[32:47], v[64:67], v[76:79], v[32:47]
	ds_read_b128 v[104:107], v126 offset:0
	v_mfma_f32_32x32x16_bf16 v[16:31], v[68:71], v[72:75], v[16:31]
	ds_read_b128 v[108:111], v126 offset:4096
	v_mfma_f32_32x32x16_bf16 v[0:15], v[68:71], v[76:79], v[0:15]
	ds_read_b128 v[100:103], v122 offset:4096
	s_waitcnt lgkmcnt(4)
	v_mfma_f32_32x32x16_bf16 v[48:63], v[80:83], v[88:91], v[48:63]
	ds_read_b128 v[64:67], v123 offset:0
	v_mfma_f32_32x32x16_bf16 v[32:47], v[80:83], v[92:95], v[32:47]
	ds_read_b128 v[72:75], v127 offset:0
	v_mfma_f32_32x32x16_bf16 v[16:31], v[84:87], v[88:91], v[16:31]
	ds_read_b128 v[76:79], v127 offset:4096
	v_mfma_f32_32x32x16_bf16 v[0:15], v[84:87], v[92:95], v[0:15]
	ds_read_b128 v[68:71], v123 offset:4096
	s_waitcnt lgkmcnt(4)
	v_mfma_f32_32x32x16_bf16 v[48:63], v[96:99], v[104:107], v[48:63]
	v_mfma_f32_32x32x16_bf16 v[32:47], v[96:99], v[108:111], v[32:47]
	v_mfma_f32_32x32x16_bf16 v[16:31], v[100:103], v[104:107], v[16:31]
	v_mfma_f32_32x32x16_bf16 v[0:15], v[100:103], v[108:111], v[0:15]
	s_waitcnt lgkmcnt(0)
	v_mfma_f32_32x32x16_bf16 v[48:63], v[64:67], v[72:75], v[48:63]
	v_mfma_f32_32x32x16_bf16 v[32:47], v[64:67], v[76:79], v[32:47]
	v_mfma_f32_32x32x16_bf16 v[16:31], v[68:71], v[72:75], v[16:31]
	v_mfma_f32_32x32x16_bf16 v[0:15], v[68:71], v[76:79], v[0:15]
	s_barrier
	s_add_i32 s99, s57, s92
	s_mov_b32 s6, 0
	s_cmp_gt_i32 s99, 0x107f
	s_cbranch_scc1 .Lg2_nonext
	s_and_b32 s100, s99, 7
	s_bfe_u32 s101, s99, 0x60003
	s_lshr_b32 s99, s99, 9
	s_lshl_b32 s99, s99, 6
	s_add_u32 s101, s101, s99
	s_mul_hi_u32 s99, s101, 0xaaaaaaab
	s_lshr_b32 s99, s99, 3
	s_mul_i32 s6, s99, 12
	s_sub_u32 s101, s101, s6
	s_mul_i32 s100, s100, 12
	s_add_u32 s100, s100, s101
	s_lshl_b32 s100, s100, 7
	s_lshl_b32 s99, s99, 7
	s_sub_i32 s100, s100, s48
	s_sub_i32 s99, s99, s49
	s_lshr_b32 s6, s98, 13
	s_cmp_lt_u32 s6, 2
	s_cselect_b32 s6, s100, s99
	s_mul_i32 s6, s6, 0x800
	s_sub_i32 s6, s6, 0x800
	s_ashr_i32 s100, s6, 31
	s_add_u32 s2, s2, s6
	s_addc_u32 s3, s3, s100
	s_add_u32 m0, s98, 0x0
	s_nop 0
	global_load_lds_dwordx4 v112, s[2:3] offset:0
	global_load_lds_dwordx4 v113, s[2:3] offset:1024
	global_load_lds_dwordx4 v114, s[2:3] offset:2048
	global_load_lds_dwordx4 v115, s[2:3] offset:3072
	s_add_u32 m0, s98, 0x1000
	s_nop 0
	global_load_lds_dwordx4 v116, s[2:3] offset:0
	global_load_lds_dwordx4 v117, s[2:3] offset:1024
	global_load_lds_dwordx4 v118, s[2:3] offset:2048
	global_load_lds_dwordx4 v119, s[2:3] offset:3072
	s_add_u32 s2, s2, 0x80
	s_addc_u32 s3, s3, 0
	s_mov_b32 s6, 1
.Lg2_nonext:
	s_cmp_lg_u32 s6, 0
	s_cbranch_scc1 .Lg2_w15p
	s_waitcnt vmcnt(0)
	s_branch .Lg2_s15

.Lg2_s15:
	s_barrier
	ds_read_b128 v[64:67], v120 offset:32768
	ds_read_b128 v[72:75], v124 offset:32768
	ds_read_b128 v[76:79], v124 offset:36864
	ds_read_b128 v[68:71], v120 offset:36864
	ds_read_b128 v[80:83], v121 offset:32768
	ds_read_b128 v[88:91], v125 offset:32768
	ds_read_b128 v[92:95], v125 offset:36864
	ds_read_b128 v[84:87], v121 offset:36864
	s_waitcnt lgkmcnt(4)
	v_mfma_f32_32x32x16_bf16 v[48:63], v[64:67], v[72:75], v[48:63]
	ds_read_b128 v[96:99], v122 offset:32768
	v_mfma_f32_32x32x16_bf16 v[32:47], v[64:67], v[76:79], v[32:47]
	ds_read_b128 v[104:107], v126 offset:32768
	v_mfma_f32_32x32x16_bf16 v[16:31], v[68:71], v[72:75], v[16:31]
	ds_read_b128 v[108:111], v126 offset:36864
	v_mfma_f32_32x32x16_bf16 v[0:15], v[68:71], v[76:79], v[0:15]
	ds_read_b128 v[100:103], v122 offset:36864
	s_waitcnt lgkmcnt(4)
	v_mfma_f32_32x32x16_bf16 v[48:63], v[80:83], v[88:91], v[48:63]
	ds_read_b128 v[64:67], v123 offset:32768
	v_mfma_f32_32x32x16_bf16 v[32:47], v[80:83], v[92:95], v[32:47]
	ds_read_b128 v[72:75], v127 offset:32768
	v_mfma_f32_32x32x16_bf16 v[16:31], v[84:87], v[88:91], v[16:31]
	ds_read_b128 v[76:79], v127 offset:36864
	v_mfma_f32_32x32x16_bf16 v[0:15], v[84:87], v[92:95], v[0:15]
	ds_read_b128 v[68:71], v123 offset:36864
	s_waitcnt lgkmcnt(4)
	v_mfma_f32_32x32x16_bf16 v[48:63], v[96:99], v[104:107], v[48:63]
	v_mfma_f32_32x32x16_bf16 v[32:47], v[96:99], v[108:111], v[32:47]
	v_mfma_f32_32x32x16_bf16 v[16:31], v[100:103], v[104:107], v[16:31]
	v_mfma_f32_32x32x16_bf16 v[0:15], v[100:103], v[108:111], v[0:15]
	s_waitcnt lgkmcnt(0)
	v_mfma_f32_32x32x16_bf16 v[48:63], v[64:67], v[72:75], v[48:63]
	v_mfma_f32_32x32x16_bf16 v[32:47], v[64:67], v[76:79], v[32:47]
	v_mfma_f32_32x32x16_bf16 v[16:31], v[68:71], v[72:75], v[16:31]
	v_mfma_f32_32x32x16_bf16 v[0:15], v[68:71], v[76:79], v[0:15]
	s_barrier
	v_writelane_b32 v251, s6, 0
	s_cmp_lg_u32 s6, 0
	s_cbranch_scc0 .Lg2_done
	s_add_u32 m0, s98, 0x8000
	s_nop 0
	global_load_lds_dwordx4 v112, s[2:3] offset:0
	global_load_lds_dwordx4 v113, s[2:3] offset:1024
	global_load_lds_dwordx4 v114, s[2:3] offset:2048
	global_load_lds_dwordx4 v115, s[2:3] offset:3072
	s_add_u32 m0, s98, 0x9000
	s_nop 0
	global_load_lds_dwordx4 v116, s[2:3] offset:0
	global_load_lds_dwordx4 v117, s[2:3] offset:1024
	global_load_lds_dwordx4 v118, s[2:3] offset:2048
	global_load_lds_dwordx4 v119, s[2:3] offset:3072
	s_add_u32 s2, s2, 0x80
	s_addc_u32 s3, s3, 0

.LBB0_2284:
	s_and_b32 s4, s47, 7
	s_bfe_u32 s5, s47, 0x60003
	s_lshr_b32 s6, s47, 9
	s_lshl_b32 s6, s6, 6
	s_add_u32 s5, s5, s6
	s_mul_hi_u32 s6, s5, 0xaaaaaaab
	s_lshr_b32 s6, s6, 3
	s_mul_i32 s7, s6, 12
	s_sub_u32 s5, s5, s7
	s_mul_i32 s4, s4, 12
	s_add_u32 s4, s4, s5
	s_lshl_b32 s48, s4, 7
	s_lshl_b32 s49, s6, 7
	v_lshl_or_b32 v64, v183, 3, v191
	v_and_b32_e32 v65, 63, v64
	v_lshrrev_b32_e32 v66, 3, v65
	v_lshrrev_b32_e32 v67, 4, v65
	v_xor_b32_e32 v67, v67, v65
	v_and_b32_e32 v67, 7, v67
	v_lshlrev_b32_e32 v67, 4, v67
	s_movk_i32 s99, 0x800
	v_mad_u32_u24 v112, v66, s99, v67
	v_xor_b32_e32 v68, 64, v112
	v_add_u32_e32 v113, 0x3c00, v68
	v_add_u32_e32 v114, 0x7800, v112
	v_add_u32_e32 v115, 0xb400, v68
	v_add_u32_e32 v116, 0x10000, v112
	v_add_u32_e32 v117, 0x13c00, v68
	v_add_u32_e32 v118, 0x17800, v112
	v_add_u32_e32 v119, 0x1b400, v68
	v_and_b32_e32 v69, 31, v64
	v_bfe_u32 v70, v64, 5, 1
	v_bfe_u32 v71, v64, 1, 3
	v_xor_b32_e32 v71, v71, v70
	v_lshlrev_b32_e32 v71, 4, v71
	v_bfe_u32 v72, v64, 7, 1
	v_lshl_or_b32 v72, v72, 6, v69
	v_lshl_add_u32 v120, v72, 7, v71
	v_bfe_u32 v73, v64, 6, 1
	v_lshl_or_b32 v73, v73, 6, v69
	v_lshl_add_u32 v124, v73, 7, v71
	v_add_u32_e32 v124, 0x4000, v124
	v_xor_b32_e32 v121, 32, v120
	v_xor_b32_e32 v125, 32, v124
	v_xor_b32_e32 v122, 64, v120
	v_xor_b32_e32 v126, 64, v124
	v_xor_b32_e32 v123, 96, v120
	v_xor_b32_e32 v127, 96, v124
	v_lshrrev_b32_e32 v74, 6, v64
	s_nop 0
	v_readfirstlane_b32 s100, v74
	s_nop 3
	s_lshl_b32 s98, s100, 13
	s_mov_b32 s101, 0x1640000
	s_mov_b32 s99, s49
	s_cmp_lt_u32 s100, 2
	s_cmov_b32 s101, 0xb171900
	s_cmov_b32 s99, s48
	s_and_b32 s100, s100, 1
	s_lshl_b32 s100, s100, 6
	s_add_u32 s99, s99, s100
	s_mul_i32 s99, s99, 0x800
	s_add_u32 s99, s99, s101
	s_add_u32 s4, s90, s99
	s_addc_u32 s5, s91, 0
	v_readlane_b32 s99, v251, 0
	s_cmp_lg_u32 s99, 0
	s_cbranch_scc1 .Lg6_pref
	s_add_u32 m0, s98, 0x0
	s_nop 0
	global_load_lds_dwordx4 v112, s[4:5] offset:0
	global_load_lds_dwordx4 v113, s[4:5] offset:1024
	global_load_lds_dwordx4 v114, s[4:5] offset:2048
	global_load_lds_dwordx4 v115, s[4:5] offset:3072
	s_add_u32 m0, s98, 0x1000
	s_nop 0
	global_load_lds_dwordx4 v116, s[4:5] offset:0
	global_load_lds_dwordx4 v117, s[4:5] offset:1024
	global_load_lds_dwordx4 v118, s[4:5] offset:2048
	global_load_lds_dwordx4 v119, s[4:5] offset:3072
	s_add_u32 s4, s4, 0x80
	s_addc_u32 s5, s5, 0
	s_add_u32 m0, s98, 0x8000
	s_nop 0
	global_load_lds_dwordx4 v112, s[4:5] offset:0
	global_load_lds_dwordx4 v113, s[4:5] offset:1024
	global_load_lds_dwordx4 v114, s[4:5] offset:2048
	global_load_lds_dwordx4 v115, s[4:5] offset:3072
	s_add_u32 m0, s98, 0x9000
	s_nop 0
	global_load_lds_dwordx4 v116, s[4:5] offset:0
	global_load_lds_dwordx4 v117, s[4:5] offset:1024
	global_load_lds_dwordx4 v118, s[4:5] offset:2048
	global_load_lds_dwordx4 v119, s[4:5] offset:3072
	s_add_u32 s4, s4, 0x80
	s_addc_u32 s5, s5, 0
	s_mov_b32 s101, 0
	s_branch .Lg6_prol
.Lg6_pref:
	s_add_u32 s4, s4, 0x100
	s_addc_u32 s5, s5, 0
	s_mov_b32 s101, 1

.Lg6_loop:
	s_barrier
	ds_read_b128 v[64:67], v120 offset:0
	ds_read_b128 v[72:75], v124 offset:0
	ds_read_b128 v[76:79], v124 offset:4096
	ds_read_b128 v[68:71], v120 offset:4096
	ds_read_b128 v[80:83], v121 offset:0
	ds_read_b128 v[88:91], v125 offset:0
	ds_read_b128 v[92:95], v125 offset:4096
	ds_read_b128 v[84:87], v121 offset:4096
	s_waitcnt lgkmcnt(4)
	v_mfma_f32_32x32x16_bf16 v[48:63], v[64:67], v[72:75], v[48:63]
	ds_read_b128 v[96:99], v122 offset:0
	v_mfma_f32_32x32x16_bf16 v[32:47], v[64:67], v[76:79], v[32:47]
	ds_read_b128 v[104:107], v126 offset:0
	v_mfma_f32_32x32x16_bf16 v[16:31], v[68:71], v[72:75], v[16:31]
	ds_read_b128 v[108:111], v126 offset:4096
	v_mfma_f32_32x32x16_bf16 v[0:15], v[68:71], v[76:79], v[0:15]
	ds_read_b128 v[100:103], v122 offset:4096
	s_waitcnt lgkmcnt(4)
	v_mfma_f32_32x32x16_bf16 v[48:63], v[80:83], v[88:91], v[48:63]
	ds_read_b128 v[64:67], v123 offset:0
	v_mfma_f32_32x32x16_bf16 v[32:47], v[80:83], v[92:95], v[32:47]
	ds_read_b128 v[72:75], v127 offset:0
	v_mfma_f32_32x32x16_bf16 v[16:31], v[84:87], v[88:91], v[16:31]
	ds_read_b128 v[76:79], v127 offset:4096
	v_mfma_f32_32x32x16_bf16 v[0:15], v[84:87], v[92:95], v[0:15]
	ds_read_b128 v[68:71], v123 offset:4096
	s_waitcnt lgkmcnt(4)
	v_mfma_f32_32x32x16_bf16 v[48:63], v[96:99], v[104:107], v[48:63]
	v_mfma_f32_32x32x16_bf16 v[32:47], v[96:99], v[108:111], v[32:47]
	v_mfma_f32_32x32x16_bf16 v[16:31], v[100:103], v[104:107], v[16:31]
	v_mfma_f32_32x32x16_bf16 v[0:15], v[100:103], v[108:111], v[0:15]
	s_waitcnt lgkmcnt(0)
	v_mfma_f32_32x32x16_bf16 v[48:63], v[64:67], v[72:75], v[48:63]
	v_mfma_f32_32x32x16_bf16 v[32:47], v[64:67], v[76:79], v[32:47]
	v_mfma_f32_32x32x16_bf16 v[16:31], v[68:71], v[72:75], v[16:31]
	v_mfma_f32_32x32x16_bf16 v[0:15], v[68:71], v[76:79], v[0:15]
	s_barrier
	s_add_u32 m0, s98, 0x0
	s_nop 0
	global_load_lds_dwordx4 v112, s[4:5] offset:0
	global_load_lds_dwordx4 v113, s[4:5] offset:1024
	global_load_lds_dwordx4 v114, s[4:5] offset:2048
	global_load_lds_dwordx4 v115, s[4:5] offset:3072
	s_add_u32 m0, s98, 0x1000
	s_nop 0
	global_load_lds_dwordx4 v116, s[4:5] offset:0
	global_load_lds_dwordx4 v117, s[4:5] offset:1024
	global_load_lds_dwordx4 v118, s[4:5] offset:2048
	global_load_lds_dwordx4 v119, s[4:5] offset:3072
	s_add_u32 s4, s4, 0x80
	s_addc_u32 s5, s5, 0
	s_waitcnt vmcnt(8)
	s_barrier
	ds_read_b128 v[64:67], v120 offset:32768
	ds_read_b128 v[72:75], v124 offset:32768
	ds_read_b128 v[76:79], v124 offset:36864
	ds_read_b128 v[68:71], v120 offset:36864
	ds_read_b128 v[80:83], v121 offset:32768
	ds_read_b128 v[88:91], v125 offset:32768
	ds_read_b128 v[92:95], v125 offset:36864
	ds_read_b128 v[84:87], v121 offset:36864
	s_waitcnt lgkmcnt(4)
	v_mfma_f32_32x32x16_bf16 v[48:63], v[64:67], v[72:75], v[48:63]
	ds_read_b128 v[96:99], v122 offset:32768
	v_mfma_f32_32x32x16_bf16 v[32:47], v[64:67], v[76:79], v[32:47]
	ds_read_b128 v[104:107], v126 offset:32768
	v_mfma_f32_32x32x16_bf16 v[16:31], v[68:71], v[72:75], v[16:31]
	ds_read_b128 v[108:111], v126 offset:36864
	v_mfma_f32_32x32x16_bf16 v[0:15], v[68:71], v[76:79], v[0:15]
	ds_read_b128 v[100:103], v122 offset:36864
	s_waitcnt lgkmcnt(4)
	v_mfma_f32_32x32x16_bf16 v[48:63], v[80:83], v[88:91], v[48:63]
	ds_read_b128 v[64:67], v123 offset:32768
	v_mfma_f32_32x32x16_bf16 v[32:47], v[80:83], v[92:95], v[32:47]
	ds_read_b128 v[72:75], v127 offset:32768
	v_mfma_f32_32x32x16_bf16 v[16:31], v[84:87], v[88:91], v[16:31]
	ds_read_b128 v[76:79], v127 offset:36864
	v_mfma_f32_32x32x16_bf16 v[0:15], v[84:87], v[92:95], v[0:15]
	ds_read_b128 v[68:71], v123 offset:36864
	s_waitcnt lgkmcnt(4)
	v_mfma_f32_32x32x16_bf16 v[48:63], v[96:99], v[104:107], v[48:63]
	v_mfma_f32_32x32x16_bf16 v[32:47], v[96:99], v[108:111], v[32:47]
	v_mfma_f32_32x32x16_bf16 v[16:31], v[100:103], v[104:107], v[16:31]
	v_mfma_f32_32x32x16_bf16 v[0:15], v[100:103], v[108:111], v[0:15]
	s_waitcnt lgkmcnt(0)
	v_mfma_f32_32x32x16_bf16 v[48:63], v[64:67], v[72:75], v[48:63]
	v_mfma_f32_32x32x16_bf16 v[32:47], v[64:67], v[76:79], v[32:47]
	v_mfma_f32_32x32x16_bf16 v[16:31], v[68:71], v[72:75], v[16:31]
	v_mfma_f32_32x32x16_bf16 v[0:15], v[68:71], v[76:79], v[0:15]
	s_barrier
	s_add_u32 m0, s98, 0x8000
	s_nop 0
	global_load_lds_dwordx4 v112, s[4:5] offset:0
	global_load_lds_dwordx4 v113, s[4:5] offset:1024
	global_load_lds_dwordx4 v114, s[4:5] offset:2048
	global_load_lds_dwordx4 v115, s[4:5] offset:3072
	s_add_u32 m0, s98, 0x9000
	s_nop 0
	global_load_lds_dwordx4 v116, s[4:5] offset:0
	global_load_lds_dwordx4 v117, s[4:5] offset:1024
	global_load_lds_dwordx4 v118, s[4:5] offset:2048
	global_load_lds_dwordx4 v119, s[4:5] offset:3072
	s_add_u32 s4, s4, 0x80
	s_addc_u32 s5, s5, 0
	s_sub_u32 s6, s6, 1
	s_waitcnt vmcnt(8)
	s_cmp_lg_u32 s6, 0
	s_cbranch_scc1 .Lg6_loop
	s_barrier
	ds_read_b128 v[64:67], v120 offset:0
	ds_read_b128 v[72:75], v124 offset:0
	ds_read_b128 v[76:79], v124 offset:4096
	ds_read_b128 v[68:71], v120 offset:4096
	ds_read_b128 v[80:83], v121 offset:0
	ds_read_b128 v[88:91], v125 offset:0
	ds_read_b128 v[92:95], v125 offset:4096
	ds_read_b128 v[84:87], v121 offset:4096
	s_waitcnt lgkmcnt(4)
	v_mfma_f32_32x32x16_bf16 v[48:63], v[64:67], v[72:75], v[48:63]
	ds_read_b128 v[96:99], v122 offset:0
	v_mfma_f32_32x32x16_bf16 v[32:47], v[64:67], v[76:79], v[32:47]
	ds_read_b128 v[104:107], v126 offset:0
	v_mfma_f32_32x32x16_bf16 v[16:31], v[68:71], v[72:75], v[16:31]
	ds_read_b128 v[108:111], v126 offset:4096
	v_mfma_f32_32x32x16_bf16 v[0:15], v[68:71], v[76:79], v[0:15]
	ds_read_b128 v[100:103], v122 offset:4096
	s_waitcnt lgkmcnt(4)
	v_mfma_f32_32x32x16_bf16 v[48:63], v[80:83], v[88:91], v[48:63]
	ds_read_b128 v[64:67], v123 offset:0
	v_mfma_f32_32x32x16_bf16 v[32:47], v[80:83], v[92:95], v[32:47]
	ds_read_b128 v[72:75], v127 offset:0
	v_mfma_f32_32x32x16_bf16 v[16:31], v[84:87], v[88:91], v[16:31]
	ds_read_b128 v[76:79], v127 offset:4096
	v_mfma_f32_32x32x16_bf16 v[0:15], v[84:87], v[92:95], v[0:15]
	ds_read_b128 v[68:71], v123 offset:4096
	s_waitcnt lgkmcnt(4)
	v_mfma_f32_32x32x16_bf16 v[48:63], v[96:99], v[104:107], v[48:63]
	v_mfma_f32_32x32x16_bf16 v[32:47], v[96:99], v[108:111], v[32:47]
	v_mfma_f32_32x32x16_bf16 v[16:31], v[100:103], v[104:107], v[16:31]
	v_mfma_f32_32x32x16_bf16 v[0:15], v[100:103], v[108:111], v[0:15]
	s_waitcnt lgkmcnt(0)
	v_mfma_f32_32x32x16_bf16 v[48:63], v[64:67], v[72:75], v[48:63]
	v_mfma_f32_32x32x16_bf16 v[32:47], v[64:67], v[76:79], v[32:47]
	v_mfma_f32_32x32x16_bf16 v[16:31], v[68:71], v[72:75], v[16:31]
	v_mfma_f32_32x32x16_bf16 v[0:15], v[68:71], v[76:79], v[0:15]
	s_barrier
	s_add_i32 s99, s47, s92
	s_mov_b32 s6, 0
	s_cmp_gt_i32 s99, 0x107f
	s_cbranch_scc1 .Lg6_nonext
	s_and_b32 s100, s99, 7
	s_bfe_u32 s101, s99, 0x60003
	s_lshr_b32 s99, s99, 9
	s_lshl_b32 s99, s99, 6
	s_add_u32 s101, s101, s99
	s_mul_hi_u32 s99, s101, 0xaaaaaaab
	s_lshr_b32 s99, s99, 3
	s_mul_i32 s6, s99, 12
	s_sub_u32 s101, s101, s6
	s_mul_i32 s100, s100, 12
	s_add_u32 s100, s100, s101
	s_lshl_b32 s100, s100, 7
	s_lshl_b32 s99, s99, 7
	s_sub_i32 s100, s100, s48
	s_sub_i32 s99, s99, s49
	s_lshr_b32 s6, s98, 13
	s_cmp_lt_u32 s6, 2
	s_cselect_b32 s6, s100, s99
	s_mul_i32 s6, s6, 0x800
	s_sub_i32 s6, s6, 0x800
	s_ashr_i32 s100, s6, 31
	s_add_u32 s4, s4, s6
	s_addc_u32 s5, s5, s100
	s_add_u32 m0, s98, 0x0
	s_nop 0
	global_load_lds_dwordx4 v112, s[4:5] offset:0
	global_load_lds_dwordx4 v113, s[4:5] offset:1024
	global_load_lds_dwordx4 v114, s[4:5] offset:2048
	global_load_lds_dwordx4 v115, s[4:5] offset:3072
	s_add_u32 m0, s98, 0x1000
	s_nop 0
	global_load_lds_dwordx4 v116, s[4:5] offset:0
	global_load_lds_dwordx4 v117, s[4:5] offset:1024
	global_load_lds_dwordx4 v118, s[4:5] offset:2048
	global_load_lds_dwordx4 v119, s[4:5] offset:3072
	s_add_u32 s4, s4, 0x80
	s_addc_u32 s5, s5, 0
	s_mov_b32 s6, 1

.Lg6_s15:
	s_barrier
	ds_read_b128 v[64:67], v120 offset:32768
	ds_read_b128 v[72:75], v124 offset:32768
	ds_read_b128 v[76:79], v124 offset:36864
	ds_read_b128 v[68:71], v120 offset:36864
	ds_read_b128 v[80:83], v121 offset:32768
	ds_read_b128 v[88:91], v125 offset:32768
	ds_read_b128 v[92:95], v125 offset:36864
	ds_read_b128 v[84:87], v121 offset:36864
	s_waitcnt lgkmcnt(4)
	v_mfma_f32_32x32x16_bf16 v[48:63], v[64:67], v[72:75], v[48:63]
	ds_read_b128 v[96:99], v122 offset:32768
	v_mfma_f32_32x32x16_bf16 v[32:47], v[64:67], v[76:79], v[32:47]
	ds_read_b128 v[104:107], v126 offset:32768
	v_mfma_f32_32x32x16_bf16 v[16:31], v[68:71], v[72:75], v[16:31]
	ds_read_b128 v[108:111], v126 offset:36864
	v_mfma_f32_32x32x16_bf16 v[0:15], v[68:71], v[76:79], v[0:15]
	ds_read_b128 v[100:103], v122 offset:36864
	s_waitcnt lgkmcnt(4)
	v_mfma_f32_32x32x16_bf16 v[48:63], v[80:83], v[88:91], v[48:63]
	ds_read_b128 v[64:67], v123 offset:32768
	v_mfma_f32_32x32x16_bf16 v[32:47], v[80:83], v[92:95], v[32:47]
	ds_read_b128 v[72:75], v127 offset:32768
	v_mfma_f32_32x32x16_bf16 v[16:31], v[84:87], v[88:91], v[16:31]
	ds_read_b128 v[76:79], v127 offset:36864
	v_mfma_f32_32x32x16_bf16 v[0:15], v[84:87], v[92:95], v[0:15]
	ds_read_b128 v[68:71], v123 offset:36864
	s_waitcnt lgkmcnt(4)
	v_mfma_f32_32x32x16_bf16 v[48:63], v[96:99], v[104:107], v[48:63]
	v_mfma_f32_32x32x16_bf16 v[32:47], v[96:99], v[108:111], v[32:47]
	v_mfma_f32_32x32x16_bf16 v[16:31], v[100:103], v[104:107], v[16:31]
	v_mfma_f32_32x32x16_bf16 v[0:15], v[100:103], v[108:111], v[0:15]
	s_waitcnt lgkmcnt(0)
	v_mfma_f32_32x32x16_bf16 v[48:63], v[64:67], v[72:75], v[48:63]
	v_mfma_f32_32x32x16_bf16 v[32:47], v[64:67], v[76:79], v[32:47]
	v_mfma_f32_32x32x16_bf16 v[16:31], v[68:71], v[72:75], v[16:31]
	v_mfma_f32_32x32x16_bf16 v[0:15], v[68:71], v[76:79], v[0:15]
	s_barrier
	v_writelane_b32 v251, s6, 0
	s_cmp_lg_u32 s6, 0
	s_cbranch_scc0 .Lg6_done
	s_add_u32 m0, s98, 0x8000
	s_nop 0
	global_load_lds_dwordx4 v112, s[4:5] offset:0
	global_load_lds_dwordx4 v113, s[4:5] offset:1024
	global_load_lds_dwordx4 v114, s[4:5] offset:2048
	global_load_lds_dwordx4 v115, s[4:5] offset:3072
	s_add_u32 m0, s98, 0x9000
	s_nop 0
	global_load_lds_dwordx4 v116, s[4:5] offset:0
	global_load_lds_dwordx4 v117, s[4:5] offset:1024
	global_load_lds_dwordx4 v118, s[4:5] offset:2048
	global_load_lds_dwordx4 v119, s[4:5] offset:3072
	s_add_u32 s4, s4, 0x80
	s_addc_u32 s5, s5, 0
